# w24 with the fl_phase-done signal moved after the second GEMM prologue barrier (follows every wave's vmcnt wait; the atomic no longer precedes the K-tile-1 stage)
# speedup vs baseline: 1.0016x; 1.0016x over previous
; #define PG8_STAGE(bufoff, gbase, voff) do { _Pragma("unroll") for (int _i = 0; _i < 2; ++_i) \
;         __builtin_amdgcn_global_load_lds((const unsigned*)((const char*)(gbase) + (voff)[_i]), (PG8_LAS unsigned*)(lds + (bufoff) + ldsw + _i * 8192), 16, 0, 0); } while (0)
; #define PG8_WAIT_V(n) asm volatile("s_waitcnt vmcnt(" #n ")" ::: "memory")
; #define PG8_BAR __builtin_amdgcn_s_barrier()
; template <class Epi, class Sched, bool ALIGN_EPI = false, bool SP2 = false>
; __device__ __forceinline__ void gemm_phase(PG8_LAS unsigned char* lds, const Gemm g, const Sched& S, const Epi& E) {
;     ...
;         PG8_STAGE(PG8_SB(0, 0), cB, voffB); PG8_STAGE(PG8_SB(0, 1), cB + hstep, voffB); PG8_STAGE(PG8_SA(0, 0), cA, voffA); PG8_STAGE(PG8_SA(0, 1), cA + hstep, voffA);
;         if (wr == 1) PG8_BAR;
;         PG8_WAIT_V(2); PG8_BAR;
;         PG8_STAGE(PG8_SB(1, 0), cB + kstep, voffB); PG8_STAGE(PG8_SA(1, 0), cA + kstep, voffA); PG8_STAGE(PG8_SB(1, 1), cB + hstep + kstep, voffB);
;         PG8_WAIT_V(6); PG8_BAR;
.LBB0_627:
	s_mov_b64 s[46:47], 0x80
	s_and_b32 s77, s17, 3
	s_add_i32 m0, s61, 0x18000
	v_lshl_add_u64 v[6:7], v[6:7], 0, s[46:47]
	s_lshl_b32 s17, s18, 13
	s_lshl_b32 s19, s77, 5
	s_lshl_b32 s24, s77, 12
	s_waitcnt vmcnt(2)
	s_barrier
	global_load_lds_dwordx4 v[6:7], off
	v_lshl_add_u64 v[2:3], v[2:3], 0, s[46:47]
	s_add_i32 m0, s61, 0x1a000
	s_add_i32 s78, s61, 0x8000
	s_add_i32 s79, s61, 0xa000
	global_load_lds_dwordx4 v[2:3], off
	v_lshl_add_u64 v[0:1], v[0:1], 0, s[46:47]
	s_mov_b32 m0, s78
	s_add_u32 s14, s40, 0x40080
	global_load_lds_dwordx4 v[0:1], off
	v_lshl_add_u64 v[0:1], v[4:5], 0, s[46:47]
	s_mov_b32 m0, s79
	s_addc_u32 s15, s41, 0
	global_load_lds_dwordx4 v[0:1], off
	s_add_i32 m0, s61, 0x1c000
	v_lshl_add_u64 v[0:1], s[14:15], 0, v[162:163]
	global_load_lds_dwordx4 v[0:1], off
	v_lshl_add_u64 v[0:1], s[14:15], 0, v[166:167]
	s_add_i32 m0, s61, 0x1e000
	s_cmpk_lt_u32 s16, 0x100
	global_load_lds_dwordx4 v[0:1], off
	v_lshrrev_b32_e32 v1, 1, v8
	v_and_b32_e32 v170, 24, v1
	v_and_b32_e32 v0, 15, v8
	v_lshlrev_b32_e32 v1, 1, v170
	v_lshl_or_b32 v171, s18, 6, v0
	v_lshl_or_b32 v0, v0, 6, v1
	v_lshlrev_b32_e32 v1, 2, v8
	v_and_b32_e32 v1, 32, v1
	v_bitop3_b32 v2, v0, s17, v1 bitop3:0xde
	v_bitop3_b32 v197, v0, s24, v1 bitop3:0xde
	v_lshlrev_b32_e32 v0, 14, v9
	v_and_b32_e32 v0, 0xffff8000, v0
	v_lshl_add_u32 v0, v10, 11, v0
	v_and_b32_e32 v1, 1, v9
	v_lshl_or_b32 v0, v1, 6, v0
	v_lshl_add_u32 v176, v11, 1, v0
	v_lshlrev_b32_e32 v0, 14, v12
	v_and_b32_e32 v0, 0xffff8000, v0
	s_waitcnt vmcnt(6)
	v_lshl_add_u32 v0, v13, 11, v0
	v_and_b32_e32 v1, 1, v12
	s_cselect_b64 s[48:49], -1, 0
	v_lshlrev_b32_e32 v168, 2, v170
	v_lshl_or_b32 v0, v1, 6, v0
	s_add_i32 s80, 0, 0x10000
	s_add_i32 s81, 0, 0x14000
	v_lshl_add_u64 v[172:173], s[64:65], 0, v[168:169]
	v_lshl_add_u64 v[174:175], s[62:63], 0, v[168:169]
	v_mov_b32_e32 v177, v169
	v_lshl_add_u32 v178, v14, 1, v0
	v_mov_b32_e32 v179, v169
	v_mov_b64_e32 v[180:181], 0x400
	v_mov_b64_e32 v[182:183], 0x3ff
	v_add_u32_e32 v198, s80, v197
	v_add_u32_e32 v199, s81, v197
	v_add_u32_e32 v200, 0, v2
	s_mov_b32 s50, 0x3e38aa3b
	s_lshl_b32 s82, s19, 2
	v_lshlrev_b32_e32 v168, 2, v170
	v_mov_b32_e32 v201, 0x358637bd
	s_barrier
	s_and_saveexec_b64 s[100:101], s[92:93]
	s_cbranch_execz .Lp8_sig_done
	v_mov_b32_e32 v250, 0
	v_mov_b32_e32 v251, 1
	global_atomic_add v250, v251, s[10:11] offset:3072
